# mLSTM chunk loop: gate reads/exps hoisted before the S^T MFMA chain, permlane-swap row sums instead of 2 ds_bpermute
# speedup vs baseline: 1.0091x; 1.0091x over previous
; #define LAS __attribute__((address_space(3)))
; __device__ __forceinline__ unsigned pk2(float lo, float hi) { unsigned r; asm("v_cvt_pk_bf16_f32 %0, %1, %2" : "=v"(r) : "v"(lo), "v"(hi)); return r; }
; #define MFMA16(a, b, c) __builtin_amdgcn_mfma_f32_16x16x32_bf16((a), (b), (c), 0, 0, 0)
; __device__ __forceinline__ void mlstm_item(const Args& a, LAS unsigned char* L, bool sample, int b, int hh, int sl, bool dry = false) {
;     ...
;         if (wave < 4) {
;             const int st = wave >> 1, tt = wave & 1, t = tt * 16 + lr;
;             f32x4 s = (f32x4){0.f, 0.f, 0.f, 0.f};
;             if (!(st == 1 && tt == 0)) {
;                 bf16x8 Af[8], Bf[8];
; #pragma unroll
;                 for (int kk = 0; kk < 8; ++kk) { Af[kk] = *(const LAS bf16x8*)(L + L_KS + (st * 16 + lr) * 528 + kk * 64 + g * 16); Bf[kk] = *(const LAS bf16x8*)(L + L_QS + t * 528 + kk * 64 + g * 16); }
;                 __builtin_amdgcn_sched_barrier(0);
; #pragma unroll
;                 for (int kk = 0; kk < 8; ++kk) s = MFMA16(Af[kk], Bf[kk], s);
;             }
;             const float fmt = GFM[c * 32 + t];
;             const f32x4 as4 = *(const LAS f32x4*)(L + L_GAA + (c * 32 + st * 16 + g * 4) * 4);
;             float val[4];
; #pragma unroll
;             for (int j = 0; j < 4; ++j) { const int si = st * 16 + g * 4 + j; const float e = __expf(fminf(fmt + as4[j], 0.f)); val[j] = (si <= t) ? s[j] * e : 0.f; }
;             *(LAS u32x2*)(L + L_SS + t * 80 + (st * 16 + g * 4) * 2) = (u32x2){pk2(val[0], val[1]), pk2(val[2], val[3])};
;             float rsum = (val[0] + val[1]) + (val[2] + val[3]);
;             rsum += __shfl_xor(rsum, 16); rsum += __shfl_xor(rsum, 32);
;             if (g == 0) *(LAS float*)(L + L_NQ + (st * 32 + t) * 4) = rsum;
.LBB0_671:
	s_andn2_b64 vcc, exec, s[72:73]
	s_cbranch_vccnz .LBB0_661
	v_mov_b32_e32 v56, 0
	v_mov_b32_e32 v57, 0
	v_mov_b32_e32 v58, 0
	v_mov_b32_e32 v59, 0
	v_add_u32_e32 v116, 0, v110
	v_add_u32_e32 v116, 0x16500, v116
	v_add_u32_e32 v117, 0, v111
	ds_read_b32 v190, v116
	ds_read_b128 v[192:195], v117
	s_andn2_b64 vcc, exec, s[64:65]
	s_cbranch_vccnz .Lml_s3_nomma
	v_add_u32_e32 v164, v101, v99
	v_add_u32_e32 v172, v100, v99
	ds_read_b128 v[56:59], v164 offset:16896
	ds_read_b128 v[116:119], v164 offset:16960
	ds_read_b128 v[120:123], v172
	ds_read_b128 v[124:127], v172 offset:64
	ds_read_b128 v[128:131], v164 offset:17024
	ds_read_b128 v[132:135], v164 offset:17088
	ds_read_b128 v[136:139], v172 offset:128
	ds_read_b128 v[140:143], v172 offset:192
	ds_read_b128 v[144:147], v164 offset:17152
	ds_read_b128 v[148:151], v164 offset:17216
	ds_read_b128 v[152:155], v172 offset:256
	ds_read_b128 v[156:159], v172 offset:320
	ds_read_b128 v[160:163], v164 offset:17280
	ds_read_b128 v[164:167], v164 offset:17344
	ds_read_b128 v[168:171], v172 offset:384
	ds_read_b128 v[172:175], v172 offset:448
	s_waitcnt lgkmcnt(15)
	v_add_f32_e32 v196, v190, v192
	v_add_f32_e32 v197, v190, v193
	v_add_f32_e32 v198, v190, v194
	v_add_f32_e32 v199, v190, v195
	v_min_f32_e32 v196, 0, v196
	v_min_f32_e32 v197, 0, v197
	v_min_f32_e32 v198, 0, v198
	v_min_f32_e32 v199, 0, v199
	v_mul_f32_e32 v196, 0x3fb8aa3b, v196
	v_mul_f32_e32 v197, 0x3fb8aa3b, v197
	v_mul_f32_e32 v198, 0x3fb8aa3b, v198
	v_mul_f32_e32 v199, 0x3fb8aa3b, v199
	v_exp_f32_e32 v196, v196
	v_exp_f32_e32 v197, v197
	v_exp_f32_e32 v198, v198
	v_exp_f32_e32 v199, v199
	s_waitcnt lgkmcnt(13)
	v_mfma_f32_16x16x32_bf16 v[56:59], v[56:59], v[120:123], 0
	s_waitcnt lgkmcnt(12)
	v_mfma_f32_16x16x32_bf16 v[56:59], v[116:119], v[124:127], v[56:59]
	s_waitcnt lgkmcnt(9)
	v_mfma_f32_16x16x32_bf16 v[56:59], v[128:131], v[136:139], v[56:59]
	s_waitcnt lgkmcnt(8)
	v_mfma_f32_16x16x32_bf16 v[56:59], v[132:135], v[140:143], v[56:59]
	s_waitcnt lgkmcnt(5)
	v_mfma_f32_16x16x32_bf16 v[56:59], v[144:147], v[152:155], v[56:59]
	s_waitcnt lgkmcnt(4)
	v_mfma_f32_16x16x32_bf16 v[56:59], v[148:151], v[156:159], v[56:59]
	s_waitcnt lgkmcnt(1)
	v_mfma_f32_16x16x32_bf16 v[56:59], v[160:163], v[168:171], v[56:59]
	s_waitcnt lgkmcnt(0)
	v_mfma_f32_16x16x32_bf16 v[56:59], v[164:167], v[172:175], v[56:59]
	s_nop 7
	s_branch .LBB0_674
.Lml_s3_nomma:
	s_waitcnt lgkmcnt(0)
	v_add_f32_e32 v196, v190, v192
	v_add_f32_e32 v197, v190, v193
	v_add_f32_e32 v198, v190, v194
	v_add_f32_e32 v199, v190, v195
	v_min_f32_e32 v196, 0, v196
	v_min_f32_e32 v197, 0, v197
	v_min_f32_e32 v198, 0, v198
	v_min_f32_e32 v199, 0, v199
	v_mul_f32_e32 v196, 0x3fb8aa3b, v196
	v_mul_f32_e32 v197, 0x3fb8aa3b, v197
	v_mul_f32_e32 v198, 0x3fb8aa3b, v198
	v_mul_f32_e32 v199, 0x3fb8aa3b, v199
	v_exp_f32_e32 v196, v196
	v_exp_f32_e32 v197, v197
	v_exp_f32_e32 v198, v198
	v_exp_f32_e32 v199, v199
.LBB0_674:
	v_mul_f32_e32 v56, v56, v196
	v_cndmask_b32_e64 v116, v56, 0, s[12:13]
	v_mul_f32_e32 v57, v57, v197
	v_cndmask_b32_e64 v118, 0, v57, s[8:9]
	v_mul_f32_e32 v56, v58, v198
	v_cndmask_b32_e64 v119, v56, 0, s[10:11]
	v_mul_f32_e32 v56, v59, v199
	v_cndmask_b32_e64 v59, v56, 0, s[6:7]
	v_add_f32_e32 v56, v116, v118
	v_add_f32_e32 v57, v119, v59
	v_add_f32_e32 v56, v56, v57
	v_cvt_pk_bf16_f32 v59, v119, v59
	v_cvt_pk_bf16_f32 v58, v116, v118
	v_add_u32_e32 v116, v93, v94
	ds_write_b64 v116, v[58:59] offset:46592
	v_mov_b32_e32 v57, v56
	s_nop 1
	v_permlane16_swap_b32_e32 v57, v56
	v_add_f32_e32 v56, v56, v57
	v_mov_b32_e32 v57, v56
	s_nop 1
	v_permlane32_swap_b32_e32 v57, v56
	v_add_f32_e32 v56, v56, v57
	s_and_saveexec_b64 s[72:73], s[4:5]
	s_cbranch_execz .LBB0_660
	v_add_u32_e32 v57, s86, v92
	ds_write_b32 v57, v56
	s_branch .LBB0_660
